# grid barriers: the leader thread's L1 invalidate (buffer_inv sc1) issued at arrival, behind the workgroup's arrival barrier (no wave of the CU loads data again until the barrier completes; polls are s
# speedup vs baseline: 1.0135x; 1.0135x over previous
.LBB0_1467:
	s_cmp_gt_i32 s87, 1
	s_cselect_b64 s[2:3], -1, 0
	s_and_b64 s[0:1], s[6:7], s[2:3]
	s_andn2_b64 vcc, exec, s[0:1]
	s_cbranch_vccnz .LBB0_1521
	s_waitcnt vmcnt(0)
	s_waitcnt lgkmcnt(0)
	s_barrier
	s_mov_b64 s[0:1], exec
	v_readlane_b32 s4, v251, 1
	v_readlane_b32 s5, v251, 2
	s_and_b64 s[4:5], s[0:1], s[4:5]
	s_mov_b64 exec, s[4:5]
	s_cbranch_execz .LBB0_1520
	s_add_i32 s4, 0, 0x23fc0
	v_mov_b32_e32 v0, s4
	s_waitcnt vmcnt(0) expcnt(0) lgkmcnt(0)
	buffer_inv sc1
	ds_read_b32 v2, v0
	s_add_i32 s4, 0, 0x23fc4
	v_mov_b32_e32 v0, s4
	ds_read_b32 v0, v0
	s_waitcnt lgkmcnt(1)
	v_cmp_ne_u32_e32 vcc, 0, v2
	s_cbranch_vccnz .LBB0_1484
	v_readlane_b32 s4, v251, 0
	s_mul_i32 s18, s93, s4
	s_add_u32 s4, s96, 0x1000
	s_addc_u32 s5, s97, 0
	s_add_u32 s6, s96, 0x1100
	s_addc_u32 s7, s97, 0
	s_add_u32 s8, s96, 0x1200
	s_addc_u32 s9, s97, 0
	s_add_u32 s10, s96, 0x1300
	s_mul_i32 s18, s18, s92
	s_addc_u32 s11, s97, 0
	s_mov_b32 s19, 1
	v_mov_b32_e32 v16, 0
	s_branch .LBB0_1472

.LBB0_1499:
	s_or_b64 exec, exec, s[8:9]
	s_waitcnt vmcnt(0)
.LBB0_1500:
	s_andn2_saveexec_b64 s[6:7], s[6:7]
	s_cbranch_execz .LBB0_1520
	s_mov_b64 s[6:7], exec
	buffer_wbl2 sc1
	s_waitcnt lgkmcnt(0)
	s_waitcnt vmcnt(0)
	v_mbcnt_lo_u32_b32 v1, s6, 0
	v_mbcnt_hi_u32_b32 v1, s7, v1
	v_cmp_eq_u32_e32 vcc, 0, v1
	s_and_saveexec_b64 s[8:9], vcc
	s_cbranch_execz .LBB0_1503
	s_bcnt1_i32_b64 s6, s[6:7]
	v_mov_b32_e32 v2, 0x3000
	v_mov_b32_e32 v3, s6
	global_atomic_add v2, v2, v3, s[96:97] offset:1024 sc0

.LBB0_1517:
	s_or_b64 exec, exec, s[6:7]
	s_mov_b64 s[6:7], exec
	v_mbcnt_lo_u32_b32 v0, s6, 0
	v_mbcnt_hi_u32_b32 v0, s7, v0
	v_cmp_eq_u32_e32 vcc, 0, v0
	s_waitcnt vmcnt(0)
	s_and_saveexec_b64 s[8:9], vcc
	s_cbranch_execz .LBB0_1519
	s_bcnt1_i32_b64 s6, s[6:7]
	v_mov_b32_e32 v0, 0x2000
	v_mov_b32_e32 v1, s6
	global_atomic_add v0, v1, s[4:5] offset:1024
.LBB0_1519:
	s_or_b64 exec, exec, s[8:9]
.LBB0_1520:
	s_or_b64 exec, exec, s[0:1]
	s_waitcnt lgkmcnt(0)
	s_barrier

.LBB0_1696:
	s_cmp_gt_i32 s87, 2
	s_cselect_b64 s[2:3], -1, 0
	s_and_b64 s[0:1], s[0:1], s[2:3]
	s_andn2_b64 vcc, exec, s[0:1]
	s_cbranch_vccnz .LBB0_1750
	s_waitcnt vmcnt(0)
	s_waitcnt vmcnt(0) lgkmcnt(0)
	s_barrier
	s_mov_b64 s[0:1], exec
	v_readlane_b32 s4, v251, 1
	v_readlane_b32 s5, v251, 2
	s_and_b64 s[4:5], s[0:1], s[4:5]
	s_mov_b64 exec, s[4:5]
	s_cbranch_execz .LBB0_1749
	s_add_i32 s4, 0, 0x23fc0
	v_mov_b32_e32 v0, s4
	s_waitcnt vmcnt(0) expcnt(0) lgkmcnt(0)
	buffer_inv sc1
	ds_read_b32 v2, v0
	s_add_i32 s4, 0, 0x23fc4
	v_mov_b32_e32 v0, s4
	ds_read_b32 v0, v0
	s_waitcnt lgkmcnt(1)
	v_cmp_ne_u32_e32 vcc, 0, v2
	s_cbranch_vccnz .LBB0_1713
	v_readlane_b32 s4, v251, 0
	s_mul_i32 s18, s93, s4
	s_add_u32 s4, s96, 0x1000
	s_addc_u32 s5, s97, 0
	s_add_u32 s6, s96, 0x1100
	s_addc_u32 s7, s97, 0
	s_add_u32 s8, s96, 0x1200
	s_addc_u32 s9, s97, 0
	s_add_u32 s10, s96, 0x1300
	s_mul_i32 s18, s18, s92
	s_addc_u32 s11, s97, 0
	s_mov_b32 s19, 1
	v_mov_b32_e32 v16, 0
	s_branch .LBB0_1701

.LBB0_1728:
	s_or_b64 exec, exec, s[8:9]
	s_waitcnt vmcnt(0)
.LBB0_1729:
	s_andn2_saveexec_b64 s[6:7], s[6:7]
	s_cbranch_execz .LBB0_1749
	s_mov_b64 s[6:7], exec
	buffer_wbl2 sc1
	s_waitcnt lgkmcnt(0)
	s_waitcnt vmcnt(0)
	v_mbcnt_lo_u32_b32 v1, s6, 0
	v_mbcnt_hi_u32_b32 v1, s7, v1
	v_cmp_eq_u32_e32 vcc, 0, v1
	s_and_saveexec_b64 s[8:9], vcc
	s_cbranch_execz .LBB0_1732
	s_bcnt1_i32_b64 s6, s[6:7]
	v_mov_b32_e32 v2, 0x3000
	v_mov_b32_e32 v3, s6
	global_atomic_add v2, v2, v3, s[96:97] offset:1024 sc0

.LBB0_1748:
	s_or_b64 exec, exec, s[8:9]
.LBB0_1749:
	s_or_b64 exec, exec, s[0:1]
	s_waitcnt lgkmcnt(0)
	s_barrier

.LBB0_1778:
	s_cmp_gt_i32 s87, 3
	s_cselect_b64 s[0:1], -1, 0
	s_and_b64 s[2:3], s[4:5], s[0:1]
	s_waitcnt lgkmcnt(0)
	v_readlane_b32 s72, v251, 3
	s_andn2_b64 vcc, exec, s[2:3]
	v_readlane_b32 s73, v251, 4
	v_readlane_b32 s74, v251, 5
	v_readlane_b32 s75, v251, 6
	s_cbranch_vccnz .LBB0_1832
	s_waitcnt vmcnt(0)
	s_waitcnt vmcnt(0)
	s_barrier
	s_mov_b64 s[2:3], exec
	v_readlane_b32 s4, v251, 1
	v_readlane_b32 s5, v251, 2
	s_and_b64 s[4:5], s[2:3], s[4:5]
	s_mov_b64 exec, s[4:5]
	s_cbranch_execz .LBB0_1831
	s_add_i32 s4, 0, 0x23fc0
	v_mov_b32_e32 v0, s4
	s_waitcnt vmcnt(0) expcnt(0) lgkmcnt(0)
	buffer_inv sc1
	ds_read_b32 v2, v0
	s_add_i32 s4, 0, 0x23fc4
	v_mov_b32_e32 v0, s4
	ds_read_b32 v0, v0
	s_waitcnt lgkmcnt(1)
	v_cmp_ne_u32_e32 vcc, 0, v2
	s_cbranch_vccnz .LBB0_1795
	v_readlane_b32 s4, v251, 0
	s_mul_i32 s18, s93, s4
	s_add_u32 s4, s96, 0x1000
	s_addc_u32 s5, s97, 0
	s_add_u32 s6, s96, 0x1100
	s_addc_u32 s7, s97, 0
	s_add_u32 s8, s96, 0x1200
	s_addc_u32 s9, s97, 0
	s_add_u32 s10, s96, 0x1300
	s_mul_i32 s18, s18, s92
	s_addc_u32 s11, s97, 0
	s_mov_b32 s19, 1
	v_mov_b32_e32 v16, 0
	s_branch .LBB0_1783

.LBB0_1810:
	s_or_b64 exec, exec, s[8:9]
	s_waitcnt vmcnt(0)
.LBB0_1811:
	s_andn2_saveexec_b64 s[6:7], s[6:7]
	s_cbranch_execz .LBB0_1831
	s_mov_b64 s[6:7], exec
	buffer_wbl2 sc1
	s_waitcnt lgkmcnt(0)
	s_waitcnt vmcnt(0)
	v_mbcnt_lo_u32_b32 v1, s6, 0
	v_mbcnt_hi_u32_b32 v1, s7, v1
	v_cmp_eq_u32_e32 vcc, 0, v1
	s_and_saveexec_b64 s[8:9], vcc
	s_cbranch_execz .LBB0_1814
	s_bcnt1_i32_b64 s6, s[6:7]
	v_mov_b32_e32 v2, 0x3000
	v_mov_b32_e32 v3, s6
	global_atomic_add v2, v2, v3, s[96:97] offset:1024 sc0

.LBB0_1830:
	s_or_b64 exec, exec, s[8:9]
.LBB0_1831:
	s_or_b64 exec, exec, s[2:3]
	s_waitcnt lgkmcnt(0)
	s_barrier

.LBB0_1949:
	s_cmp_gt_i32 s87, 4
	s_cselect_b64 s[0:1], -1, 0
	s_and_b64 s[2:3], s[24:25], s[0:1]
	s_andn2_b64 vcc, exec, s[2:3]
	s_cbranch_vccnz .LBB0_2003
	s_waitcnt vmcnt(0)
	s_waitcnt vmcnt(0)
	s_barrier
	s_mov_b64 s[2:3], exec
	v_readlane_b32 s4, v251, 1
	v_readlane_b32 s5, v251, 2
	s_and_b64 s[4:5], s[2:3], s[4:5]
	s_mov_b64 exec, s[4:5]
	s_cbranch_execz .LBB0_2002
	s_add_i32 s4, 0, 0x23fc0
	v_mov_b32_e32 v0, s4
	s_waitcnt vmcnt(0) expcnt(0) lgkmcnt(0)
	buffer_inv sc1
	ds_read_b32 v2, v0
	s_add_i32 s4, 0, 0x23fc4
	v_mov_b32_e32 v0, s4
	ds_read_b32 v0, v0
	s_waitcnt lgkmcnt(1)
	v_cmp_ne_u32_e32 vcc, 0, v2
	s_cbranch_vccnz .LBB0_1966
	v_readlane_b32 s4, v251, 0
	s_mul_i32 s18, s93, s4
	s_add_u32 s4, s96, 0x1000
	s_addc_u32 s5, s97, 0
	s_add_u32 s6, s96, 0x1100
	s_addc_u32 s7, s97, 0
	s_add_u32 s8, s96, 0x1200
	s_addc_u32 s9, s97, 0
	s_add_u32 s10, s96, 0x1300
	s_mul_i32 s18, s18, s92
	s_addc_u32 s11, s97, 0
	s_mov_b32 s19, 1
	v_mov_b32_e32 v16, 0
	s_branch .LBB0_1954

.LBB0_1981:
	s_or_b64 exec, exec, s[8:9]
	s_waitcnt vmcnt(0)
.LBB0_1982:
	s_andn2_saveexec_b64 s[6:7], s[6:7]
	s_cbranch_execz .LBB0_2002
	s_mov_b64 s[6:7], exec
	buffer_wbl2 sc1
	s_waitcnt lgkmcnt(0)
	s_waitcnt vmcnt(0)
	v_mbcnt_lo_u32_b32 v1, s6, 0
	v_mbcnt_hi_u32_b32 v1, s7, v1
	v_cmp_eq_u32_e32 vcc, 0, v1
	s_and_saveexec_b64 s[8:9], vcc
	s_cbranch_execz .LBB0_1985
	s_bcnt1_i32_b64 s6, s[6:7]
	v_mov_b32_e32 v2, 0x3000
	v_mov_b32_e32 v3, s6
	global_atomic_add v2, v2, v3, s[96:97] offset:1024 sc0

.LBB0_2001:
	s_or_b64 exec, exec, s[8:9]
.LBB0_2002:
	s_or_b64 exec, exec, s[2:3]
	s_waitcnt lgkmcnt(0)
	s_barrier

.LBB0_2011:
	s_waitcnt vmcnt(0)
	s_waitcnt lgkmcnt(0)
	s_barrier
	s_mov_b64 s[0:1], exec
	v_readlane_b32 s2, v251, 1
	v_readlane_b32 s3, v251, 2
	v_readlane_b32 s86, v251, 48
	v_readlane_b32 s72, v251, 3
	v_readlane_b32 s66, v251, 44
	s_and_b64 s[2:3], s[0:1], s[2:3]
	v_readlane_b32 s84, v251, 40
	v_readlane_b32 s87, v251, 49
	v_readlane_b32 s88, v251, 46
	v_readlane_b32 s73, v251, 4
	v_readlane_b32 s74, v251, 5
	v_readlane_b32 s75, v251, 6
	v_readlane_b32 s90, v251, 43
	s_mov_b32 s23, s19
	v_readlane_b32 s67, v251, 45
	v_readlane_b32 s89, v251, 47
	s_mov_b64 exec, s[2:3]
	s_cbranch_execz .LBB0_2063
	s_add_u32 s2, s96, 0x200
	s_addc_u32 s3, s97, 0
	s_add_i32 s4, 0, 0x23fc0
	v_mov_b32_e32 v0, s4
	s_waitcnt vmcnt(0) expcnt(0) lgkmcnt(0)
	buffer_inv sc1
	ds_read_b32 v2, v0
	s_add_i32 s4, 0, 0x23fc4
	v_mov_b32_e32 v0, s4
	ds_read_b32 v0, v0
	s_waitcnt lgkmcnt(1)
	v_cmp_ne_u32_e32 vcc, 0, v2
	s_cbranch_vccnz .LBB0_2027
	s_mul_i32 s18, s93, s92
	v_readlane_b32 s4, v251, 0
	s_mul_i32 s18, s18, s4
	s_add_u32 s4, s96, 0x1000
	s_addc_u32 s5, s97, 0
	s_add_u32 s6, s96, 0x1100
	s_addc_u32 s7, s97, 0
	s_add_u32 s8, s96, 0x1200
	s_addc_u32 s9, s97, 0
	s_add_u32 s10, s96, 0x1300
	s_addc_u32 s11, s97, 0
	s_mov_b32 s19, 1
	v_mov_b32_e32 v16, 0
	s_branch .LBB0_2015

.LBB0_2042:
	s_or_b64 exec, exec, s[8:9]
	s_waitcnt vmcnt(0)
.LBB0_2043:
	s_andn2_saveexec_b64 s[6:7], s[6:7]
	s_cbranch_execz .LBB0_2063
	s_mov_b64 s[6:7], exec
	buffer_wbl2 sc1
	s_waitcnt lgkmcnt(0)
	s_waitcnt vmcnt(0)
	v_mbcnt_lo_u32_b32 v1, s6, 0
	v_mbcnt_hi_u32_b32 v1, s7, v1
	v_cmp_eq_u32_e32 vcc, 0, v1
	s_and_saveexec_b64 s[8:9], vcc
	s_cbranch_execz .LBB0_2046
	s_bcnt1_i32_b64 s6, s[6:7]
	v_mov_b32_e32 v2, 0x3000
	v_mov_b32_e32 v3, s6
	global_atomic_add v2, v2, v3, s[96:97] offset:1024 sc0

.LBB0_2060:
	s_or_b64 exec, exec, s[2:3]
	s_mov_b64 s[2:3], exec
	v_mbcnt_lo_u32_b32 v0, s2, 0
	v_mbcnt_hi_u32_b32 v0, s3, v0
	v_cmp_eq_u32_e32 vcc, 0, v0
	s_waitcnt vmcnt(0)
	s_and_saveexec_b64 s[6:7], vcc
	s_cbranch_execz .LBB0_2062
	s_bcnt1_i32_b64 s2, s[2:3]
	v_mov_b32_e32 v0, 0
	v_mov_b32_e32 v1, s2
	global_atomic_add v0, v1, s[4:5]
.LBB0_2062:
	s_or_b64 exec, exec, s[6:7]
.LBB0_2063:
	s_or_b64 exec, exec, s[0:1]
	s_cmpk_gt_i32 s90, 0x3ff
	v_readlane_b32 s68, v251, 50
	v_readlane_b32 s69, v251, 51
	s_waitcnt lgkmcnt(0)
	s_barrier
	s_cbranch_scc1 .LBB0_2167
	v_readlane_b32 s0, v251, 7
	v_and_b32_e32 v112, 15, v152
	v_lshrrev_b32_e32 v113, 4, v152
	s_nop 1
	s_and_b32 s34, s0, 3
	s_lshr_b32 s35, s0, 2
	v_lshrrev_b32_e32 v220, 3, v153
	v_and_b32_e32 v221, 7, v153
	v_and_b32_e32 v222, 7, v220
	v_xor_b32_e32 v222, v222, v221
	v_lshlrev_b32_e32 v222, 4, v222
	v_lshl_add_u32 v114, v220, 7, v222
	v_mul_u32_u24_e32 v123, 0x90, v220
	v_lshl_add_u32 v123, v221, 4, v123
	v_add_u32_e32 v123, 0x2400, v123
	v_mul_u32_u24_e32 v117, 0x600, v220
	v_lshl_add_u32 v117, v221, 4, v117
	v_lshlrev_b32_e32 v118, 12, v220
	v_lshl_add_u32 v118, v221, 4, v118
	v_mul_u32_u24_e32 v116, 0x90, v112
	v_lshl_add_u32 v116, v113, 3, v116
	v_and_b32_e32 v222, 7, v112
	v_xor_b32_e32 v222, v222, v113
	v_lshlrev_b32_e32 v222, 4, v222
	v_lshl_add_u32 v115, v112, 7, v222
	v_xor_b32_e32 v122, 64, v115
	s_lshl_b32 s1, s0, 13
	s_add_i32 s1, s1, 0x9000
	v_lshl_add_u32 v250, v152, 4, s1
	v_mov_b32_e32 v226, 0xf149f2ca
	v_mov_b32_e32 v227, 0xff61b1e6
	v_mov_b32_e32 v203, 0x41000000
	v_mov_b32_e32 v238, 0
	v_mov_b32_e32 v224, 0xff800000
	s_mov_b32 s26, s90
	s_mov_b32 s50, 0

.LBB0_2170:
	s_cmp_lt_i32 s87, 6
	s_cselect_b64 s[0:1], -1, 0
	s_xor_b64 s[2:3], s[66:67], -1
	s_or_b64 s[0:1], s[2:3], s[0:1]
	s_and_b64 vcc, exec, s[0:1]
	s_cbranch_vccnz .LBB0_2224
	s_waitcnt vmcnt(0)
	s_waitcnt vmcnt(0)
	s_barrier
	s_mov_b64 s[0:1], exec
	v_readlane_b32 s2, v251, 1
	v_readlane_b32 s3, v251, 2
	s_and_b64 s[2:3], s[0:1], s[2:3]
	s_mov_b64 exec, s[2:3]
	s_cbranch_execz .LBB0_2223
	s_add_i32 s2, 0, 0x23fc0
	v_mov_b32_e32 v0, s2
	s_waitcnt vmcnt(0) expcnt(0) lgkmcnt(0)
	buffer_inv sc1
	ds_read_b32 v2, v0
	s_add_i32 s2, 0, 0x23fc4
	v_mov_b32_e32 v0, s2
	ds_read_b32 v0, v0
	s_waitcnt lgkmcnt(1)
	v_cmp_ne_u32_e32 vcc, 0, v2
	s_cbranch_vccnz .LBB0_2187
	v_readlane_b32 s2, v251, 0
	s_mul_i32 s16, s93, s2
	s_add_u32 s2, s96, 0x1000
	s_addc_u32 s3, s97, 0
	s_add_u32 s4, s96, 0x1100
	s_addc_u32 s5, s97, 0
	s_add_u32 s6, s96, 0x1200
	s_addc_u32 s7, s97, 0
	s_add_u32 s8, s96, 0x1300
	s_mul_i32 s16, s16, s92
	s_addc_u32 s9, s97, 0
	s_mov_b32 s17, 1
	v_mov_b32_e32 v16, 0
	s_branch .LBB0_2175

.LBB0_2202:
	s_or_b64 exec, exec, s[6:7]
	s_waitcnt vmcnt(0)
.LBB0_2203:
	s_andn2_saveexec_b64 s[4:5], s[4:5]
	s_cbranch_execz .LBB0_2223
	s_mov_b64 s[4:5], exec
	buffer_wbl2 sc1
	s_waitcnt lgkmcnt(0)
	s_waitcnt vmcnt(0)
	v_mbcnt_lo_u32_b32 v1, s4, 0
	v_mbcnt_hi_u32_b32 v1, s5, v1
	v_cmp_eq_u32_e32 vcc, 0, v1
	s_and_saveexec_b64 s[6:7], vcc
	s_cbranch_execz .LBB0_2206
	s_bcnt1_i32_b64 s4, s[4:5]
	v_mov_b32_e32 v2, 0x3000
	v_mov_b32_e32 v3, s4
	global_atomic_add v2, v2, v3, s[96:97] offset:1024 sc0

.LBB0_2220:
	s_or_b64 exec, exec, s[4:5]
	s_mov_b64 s[4:5], exec
	v_mbcnt_lo_u32_b32 v0, s4, 0
	v_mbcnt_hi_u32_b32 v0, s5, v0
	v_cmp_eq_u32_e32 vcc, 0, v0
	s_waitcnt vmcnt(0)
	s_and_saveexec_b64 s[6:7], vcc
	s_cbranch_execz .LBB0_2222
	s_bcnt1_i32_b64 s4, s[4:5]
	v_mov_b32_e32 v0, 0x2000
	v_mov_b32_e32 v1, s4
	global_atomic_add v0, v1, s[2:3] offset:1024
.LBB0_2222:
	s_or_b64 exec, exec, s[6:7]
.LBB0_2223:
	s_or_b64 exec, exec, s[0:1]
	s_waitcnt lgkmcnt(0)
	s_barrier

.LBB0_2265:
	s_cmp_lt_i32 s87, 9
	s_cselect_b64 s[2:3], -1, 0
	s_xor_b64 s[0:1], s[0:1], -1
	s_or_b64 s[0:1], s[0:1], s[2:3]
	s_and_b64 vcc, exec, s[0:1]
	s_cbranch_vccnz .LBB0_2319
	s_waitcnt vmcnt(0)
	s_waitcnt vmcnt(0)
	s_barrier
	s_mov_b64 s[0:1], exec
	v_readlane_b32 s2, v251, 1
	v_readlane_b32 s3, v251, 2
	s_and_b64 s[2:3], s[0:1], s[2:3]
	s_mov_b64 exec, s[2:3]
	s_cbranch_execz .LBB0_2318
	s_add_i32 s2, 0, 0x23fc0
	v_mov_b32_e32 v0, s2
	s_waitcnt vmcnt(0) expcnt(0) lgkmcnt(0)
	buffer_inv sc1
	ds_read_b32 v2, v0
	s_add_i32 s2, 0, 0x23fc4
	v_mov_b32_e32 v0, s2
	ds_read_b32 v0, v0
	s_waitcnt lgkmcnt(1)
	v_cmp_ne_u32_e32 vcc, 0, v2
	s_cbranch_vccnz .LBB0_2282
	v_readlane_b32 s2, v251, 0
	s_mul_i32 s16, s93, s2
	s_add_u32 s2, s96, 0x1000
	s_addc_u32 s3, s97, 0
	s_add_u32 s4, s96, 0x1100
	s_addc_u32 s5, s97, 0
	s_add_u32 s6, s96, 0x1200
	s_addc_u32 s7, s97, 0
	s_add_u32 s8, s96, 0x1300
	s_mul_i32 s16, s16, s92
	s_addc_u32 s9, s97, 0
	s_mov_b32 s17, 1
	v_mov_b32_e32 v16, 0
	s_branch .LBB0_2270

.LBB0_2297:
	s_or_b64 exec, exec, s[6:7]
	s_waitcnt vmcnt(0)
.LBB0_2298:
	s_andn2_saveexec_b64 s[4:5], s[4:5]
	s_cbranch_execz .LBB0_2318
	s_mov_b64 s[4:5], exec
	buffer_wbl2 sc1
	s_waitcnt lgkmcnt(0)
	s_waitcnt vmcnt(0)
	v_mbcnt_lo_u32_b32 v1, s4, 0
	v_mbcnt_hi_u32_b32 v1, s5, v1
	v_cmp_eq_u32_e32 vcc, 0, v1
	s_and_saveexec_b64 s[6:7], vcc
	s_cbranch_execz .LBB0_2301
	s_bcnt1_i32_b64 s4, s[4:5]
	v_mov_b32_e32 v2, 0x3000
	v_mov_b32_e32 v3, s4
	global_atomic_add v2, v2, v3, s[96:97] offset:1024 sc0

.LBB0_2317:
	s_or_b64 exec, exec, s[6:7]
.LBB0_2318:
	s_or_b64 exec, exec, s[0:1]
	s_waitcnt lgkmcnt(0)
	s_barrier

.LBB0_2358:
	s_cmp_lt_i32 s87, 11
	s_cselect_b64 s[2:3], -1, 0
	s_xor_b64 s[0:1], s[0:1], -1
	s_or_b64 s[0:1], s[0:1], s[2:3]
	s_and_b64 vcc, exec, s[0:1]
	s_cbranch_vccnz .LBB0_2412
	s_waitcnt vmcnt(0)
	s_waitcnt vmcnt(0)
	s_barrier
	s_mov_b64 s[0:1], exec
	v_readlane_b32 s2, v251, 1
	v_readlane_b32 s3, v251, 2
	s_and_b64 s[2:3], s[0:1], s[2:3]
	s_mov_b64 exec, s[2:3]
	s_cbranch_execz .LBB0_2411
	s_add_i32 s2, 0, 0x23fc0
	v_mov_b32_e32 v0, s2
	s_waitcnt vmcnt(0) expcnt(0) lgkmcnt(0)
	buffer_inv sc1
	ds_read_b32 v2, v0
	s_add_i32 s2, 0, 0x23fc4
	v_mov_b32_e32 v0, s2
	ds_read_b32 v0, v0
	s_waitcnt lgkmcnt(1)
	v_cmp_ne_u32_e32 vcc, 0, v2
	s_cbranch_vccnz .LBB0_2375
	v_readlane_b32 s2, v251, 0
	s_mul_i32 s16, s93, s2
	s_add_u32 s2, s96, 0x1000
	s_addc_u32 s3, s97, 0
	s_add_u32 s4, s96, 0x1100
	s_addc_u32 s5, s97, 0
	s_add_u32 s6, s96, 0x1200
	s_addc_u32 s7, s97, 0
	s_add_u32 s8, s96, 0x1300
	s_mul_i32 s16, s16, s92
	s_addc_u32 s9, s97, 0
	s_mov_b32 s17, 1
	v_mov_b32_e32 v16, 0
	s_branch .LBB0_2363

.LBB0_2390:
	s_or_b64 exec, exec, s[6:7]
	s_waitcnt vmcnt(0)
.LBB0_2391:
	s_andn2_saveexec_b64 s[4:5], s[4:5]
	s_cbranch_execz .LBB0_2411
	s_mov_b64 s[4:5], exec
	buffer_wbl2 sc1
	s_waitcnt lgkmcnt(0)
	s_waitcnt vmcnt(0)
	v_mbcnt_lo_u32_b32 v1, s4, 0
	v_mbcnt_hi_u32_b32 v1, s5, v1
	v_cmp_eq_u32_e32 vcc, 0, v1
	s_and_saveexec_b64 s[6:7], vcc
	s_cbranch_execz .LBB0_2394
	s_bcnt1_i32_b64 s4, s[4:5]
	v_mov_b32_e32 v2, 0x3000
	v_mov_b32_e32 v3, s4
	global_atomic_add v2, v2, v3, s[96:97] offset:1024 sc0

.LBB0_2410:
	s_or_b64 exec, exec, s[6:7]
.LBB0_2411:
	s_or_b64 exec, exec, s[0:1]
	s_waitcnt lgkmcnt(0)
	s_barrier

.LBB0_2433:
	s_cmp_gt_i32 s87, 12
	s_cselect_b64 s[2:3], -1, 0
	s_and_b64 s[0:1], s[4:5], s[2:3]
	s_andn2_b64 vcc, exec, s[0:1]
	s_cbranch_vccnz .LBB0_2487
	s_waitcnt vmcnt(0)
	s_waitcnt vmcnt(0)
	s_barrier
	s_mov_b64 s[0:1], exec
	v_readlane_b32 s4, v251, 1
	v_readlane_b32 s5, v251, 2
	s_and_b64 s[4:5], s[0:1], s[4:5]
	s_mov_b64 exec, s[4:5]
	s_cbranch_execz .LBB0_2486
	s_add_i32 s4, 0, 0x23fc0
	v_mov_b32_e32 v0, s4
	s_waitcnt vmcnt(0) expcnt(0) lgkmcnt(0)
	buffer_inv sc1
	ds_read_b32 v2, v0
	s_add_i32 s4, 0, 0x23fc4
	v_mov_b32_e32 v0, s4
	ds_read_b32 v0, v0
	s_waitcnt lgkmcnt(1)
	v_cmp_ne_u32_e32 vcc, 0, v2
	s_cbranch_vccnz .LBB0_2450
	v_readlane_b32 s4, v251, 0
	s_mul_i32 s18, s93, s4
	s_add_u32 s4, s96, 0x1000
	s_addc_u32 s5, s97, 0
	s_add_u32 s6, s96, 0x1100
	s_addc_u32 s7, s97, 0
	s_add_u32 s8, s96, 0x1200
	s_addc_u32 s9, s97, 0
	s_add_u32 s10, s96, 0x1300
	s_mul_i32 s18, s18, s92
	s_addc_u32 s11, s97, 0
	s_mov_b32 s19, 1
	v_mov_b32_e32 v16, 0
	s_branch .LBB0_2438

.LBB0_2465:
	s_or_b64 exec, exec, s[8:9]
	s_waitcnt vmcnt(0)
.LBB0_2466:
	s_andn2_saveexec_b64 s[6:7], s[6:7]
	s_cbranch_execz .LBB0_2486
	s_mov_b64 s[6:7], exec
	buffer_wbl2 sc1
	s_waitcnt lgkmcnt(0)
	s_waitcnt vmcnt(0)
	v_mbcnt_lo_u32_b32 v1, s6, 0
	v_mbcnt_hi_u32_b32 v1, s7, v1
	v_cmp_eq_u32_e32 vcc, 0, v1
	s_and_saveexec_b64 s[8:9], vcc
	s_cbranch_execz .LBB0_2469
	s_bcnt1_i32_b64 s6, s[6:7]
	v_mov_b32_e32 v2, 0x3000
	v_mov_b32_e32 v3, s6
	global_atomic_add v2, v2, v3, s[96:97] offset:1024 sc0

.LBB0_2485:
	s_or_b64 exec, exec, s[8:9]
.LBB0_2486:
	s_or_b64 exec, exec, s[0:1]
	s_waitcnt lgkmcnt(0)
	s_barrier

.LBB0_2496:
	s_cmp_gt_i32 s87, 13
	s_cselect_b64 s[2:3], -1, 0
	s_and_b64 s[0:1], s[0:1], s[2:3]
	s_andn2_b64 vcc, exec, s[0:1]
	s_cbranch_vccnz .LBB0_2550
	s_waitcnt vmcnt(0)
	s_waitcnt vmcnt(0)
	s_barrier
	s_mov_b64 s[0:1], exec
	v_readlane_b32 s4, v251, 1
	v_readlane_b32 s5, v251, 2
	s_and_b64 s[4:5], s[0:1], s[4:5]
	s_mov_b64 exec, s[4:5]
	s_cbranch_execz .LBB0_2549
	s_add_i32 s4, 0, 0x23fc0
	v_mov_b32_e32 v0, s4
	s_waitcnt vmcnt(0) expcnt(0) lgkmcnt(0)
	buffer_inv sc1
	ds_read_b32 v2, v0
	s_add_i32 s4, 0, 0x23fc4
	v_mov_b32_e32 v0, s4
	ds_read_b32 v0, v0
	s_waitcnt lgkmcnt(1)
	v_cmp_ne_u32_e32 vcc, 0, v2
	s_cbranch_vccnz .LBB0_2513
	v_readlane_b32 s4, v251, 0
	s_mul_i32 s18, s93, s4
	s_add_u32 s4, s96, 0x1000
	s_addc_u32 s5, s97, 0
	s_add_u32 s6, s96, 0x1100
	s_addc_u32 s7, s97, 0
	s_add_u32 s8, s96, 0x1200
	s_addc_u32 s9, s97, 0
	s_add_u32 s10, s96, 0x1300
	s_mul_i32 s18, s18, s92
	s_addc_u32 s11, s97, 0
	s_mov_b32 s19, 1
	v_mov_b32_e32 v16, 0
	s_branch .LBB0_2501

.LBB0_2528:
	s_or_b64 exec, exec, s[8:9]
	s_waitcnt vmcnt(0)
.LBB0_2529:
	s_andn2_saveexec_b64 s[6:7], s[6:7]
	s_cbranch_execz .LBB0_2549
	s_mov_b64 s[6:7], exec
	buffer_wbl2 sc1
	s_waitcnt lgkmcnt(0)
	s_waitcnt vmcnt(0)
	v_mbcnt_lo_u32_b32 v1, s6, 0
	v_mbcnt_hi_u32_b32 v1, s7, v1
	v_cmp_eq_u32_e32 vcc, 0, v1
	s_and_saveexec_b64 s[8:9], vcc
	s_cbranch_execz .LBB0_2532
	s_bcnt1_i32_b64 s6, s[6:7]
	v_mov_b32_e32 v2, 0x3000
	v_mov_b32_e32 v3, s6
	global_atomic_add v2, v2, v3, s[96:97] offset:1024 sc0

.LBB0_2548:
	s_or_b64 exec, exec, s[8:9]
.LBB0_2549:
	s_or_b64 exec, exec, s[0:1]
	s_waitcnt lgkmcnt(0)
	s_barrier

.LBB0_2589:
	s_cmp_lt_i32 s87, 15
	s_cselect_b64 s[2:3], -1, 0
	s_xor_b64 s[0:1], s[0:1], -1
	s_or_b64 s[0:1], s[0:1], s[2:3]
	s_and_b64 vcc, exec, s[0:1]
	s_cbranch_vccnz .LBB0_2643
	s_waitcnt vmcnt(0)
	s_waitcnt vmcnt(0)
	s_barrier
	s_mov_b64 s[0:1], exec
	v_readlane_b32 s2, v251, 1
	v_readlane_b32 s3, v251, 2
	s_and_b64 s[2:3], s[0:1], s[2:3]
	s_mov_b64 exec, s[2:3]
	s_cbranch_execz .LBB0_2642
	s_add_i32 s2, 0, 0x23fc0
	v_mov_b32_e32 v0, s2
	s_waitcnt vmcnt(0) expcnt(0) lgkmcnt(0)
	buffer_inv sc1
	ds_read_b32 v2, v0
	s_add_i32 s2, 0, 0x23fc4
	v_mov_b32_e32 v0, s2
	ds_read_b32 v0, v0
	s_waitcnt lgkmcnt(1)
	v_cmp_ne_u32_e32 vcc, 0, v2
	s_cbranch_vccnz .LBB0_2606
	v_readlane_b32 s2, v251, 0
	s_mul_i32 s16, s93, s2
	s_add_u32 s2, s96, 0x1000
	s_addc_u32 s3, s97, 0
	s_add_u32 s4, s96, 0x1100
	s_addc_u32 s5, s97, 0
	s_add_u32 s6, s96, 0x1200
	s_addc_u32 s7, s97, 0
	s_add_u32 s8, s96, 0x1300
	s_mul_i32 s16, s16, s92
	s_addc_u32 s9, s97, 0
	s_mov_b32 s17, 1
	v_mov_b32_e32 v16, 0
	s_branch .LBB0_2594

.LBB0_2621:
	s_or_b64 exec, exec, s[6:7]
	s_waitcnt vmcnt(0)
.LBB0_2622:
	s_andn2_saveexec_b64 s[4:5], s[4:5]
	s_cbranch_execz .LBB0_2642
	s_mov_b64 s[4:5], exec
	buffer_wbl2 sc1
	s_waitcnt lgkmcnt(0)
	s_waitcnt vmcnt(0)
	v_mbcnt_lo_u32_b32 v1, s4, 0
	v_mbcnt_hi_u32_b32 v1, s5, v1
	v_cmp_eq_u32_e32 vcc, 0, v1
	s_and_saveexec_b64 s[6:7], vcc
	s_cbranch_execz .LBB0_2625
	s_bcnt1_i32_b64 s4, s[4:5]
	v_mov_b32_e32 v2, 0x3000
	v_mov_b32_e32 v3, s4
	global_atomic_add v2, v2, v3, s[96:97] offset:1024 sc0

.LBB0_2641:
	s_or_b64 exec, exec, s[6:7]
.LBB0_2642:
	s_or_b64 exec, exec, s[0:1]
	s_waitcnt lgkmcnt(0)
	s_barrier

.LBB0_2660:
	s_cmp_gt_i32 s87, 16
	s_cselect_b64 s[0:1], -1, 0
	s_and_b64 s[2:3], s[4:5], s[0:1]
	s_andn2_b64 vcc, exec, s[2:3]
	s_cbranch_vccnz .LBB0_2714
	s_waitcnt vmcnt(0)
	s_waitcnt vmcnt(0)
	s_barrier
	s_mov_b64 s[2:3], exec
	v_readlane_b32 s4, v251, 1
	v_readlane_b32 s5, v251, 2
	s_and_b64 s[4:5], s[2:3], s[4:5]
	s_mov_b64 exec, s[4:5]
	s_cbranch_execz .LBB0_2713
	s_add_i32 s4, 0, 0x23fc0
	v_mov_b32_e32 v0, s4
	s_waitcnt vmcnt(0) expcnt(0) lgkmcnt(0)
	buffer_inv sc1
	ds_read_b32 v2, v0
	s_add_i32 s4, 0, 0x23fc4
	v_mov_b32_e32 v0, s4
	ds_read_b32 v0, v0
	s_waitcnt lgkmcnt(1)
	v_cmp_ne_u32_e32 vcc, 0, v2
	s_cbranch_vccnz .LBB0_2677
	v_readlane_b32 s4, v251, 0
	s_mul_i32 s18, s93, s4
	s_add_u32 s4, s96, 0x1000
	s_addc_u32 s5, s97, 0
	s_add_u32 s6, s96, 0x1100
	s_addc_u32 s7, s97, 0
	s_add_u32 s8, s96, 0x1200
	s_addc_u32 s9, s97, 0
	s_add_u32 s10, s96, 0x1300
	s_mul_i32 s18, s18, s92
	s_addc_u32 s11, s97, 0
	s_mov_b32 s19, 1
	v_mov_b32_e32 v16, 0
	s_branch .LBB0_2665

.LBB0_2692:
	s_or_b64 exec, exec, s[8:9]
	s_waitcnt vmcnt(0)
.LBB0_2693:
	s_andn2_saveexec_b64 s[6:7], s[6:7]
	s_cbranch_execz .LBB0_2713
	s_mov_b64 s[6:7], exec
	buffer_wbl2 sc1
	s_waitcnt lgkmcnt(0)
	s_waitcnt vmcnt(0)
	v_mbcnt_lo_u32_b32 v1, s6, 0
	v_mbcnt_hi_u32_b32 v1, s7, v1
	v_cmp_eq_u32_e32 vcc, 0, v1
	s_and_saveexec_b64 s[8:9], vcc
	s_cbranch_execz .LBB0_2696
	s_bcnt1_i32_b64 s6, s[6:7]
	v_mov_b32_e32 v2, 0x3000
	v_mov_b32_e32 v3, s6
	global_atomic_add v2, v2, v3, s[96:97] offset:1024 sc0

.LBB0_2712:
	s_or_b64 exec, exec, s[8:9]
.LBB0_2713:
	s_or_b64 exec, exec, s[2:3]
	s_waitcnt lgkmcnt(0)
	s_barrier

.LBB0_2757:
	s_cmp_gt_i32 s87, 17
	s_cselect_b64 s[0:1], -1, 0
	s_and_b64 s[2:3], s[6:7], s[0:1]
	s_andn2_b64 vcc, exec, s[2:3]
	s_cbranch_vccnz .LBB0_2811
	s_waitcnt vmcnt(0)
	s_waitcnt vmcnt(0)
	s_barrier
	s_mov_b64 s[2:3], exec
	v_readlane_b32 s4, v251, 1
	v_readlane_b32 s5, v251, 2
	s_and_b64 s[4:5], s[2:3], s[4:5]
	s_mov_b64 exec, s[4:5]
	s_cbranch_execz .LBB0_2810
	s_add_i32 s4, 0, 0x23fc0
	v_mov_b32_e32 v0, s4
	s_waitcnt vmcnt(0) expcnt(0) lgkmcnt(0)
	buffer_inv sc1
	ds_read_b32 v2, v0
	s_add_i32 s4, 0, 0x23fc4
	v_mov_b32_e32 v0, s4
	ds_read_b32 v0, v0
	s_waitcnt lgkmcnt(1)
	v_cmp_ne_u32_e32 vcc, 0, v2
	s_cbranch_vccnz .LBB0_2774
	v_readlane_b32 s4, v251, 0
	s_mul_i32 s18, s93, s4
	s_add_u32 s4, s96, 0x1000
	s_addc_u32 s5, s97, 0
	s_add_u32 s6, s96, 0x1100
	s_addc_u32 s7, s97, 0
	s_add_u32 s8, s96, 0x1200
	s_addc_u32 s9, s97, 0
	s_add_u32 s10, s96, 0x1300
	s_mul_i32 s18, s18, s92
	s_addc_u32 s11, s97, 0
	s_mov_b32 s19, 1
	v_mov_b32_e32 v16, 0
	s_branch .LBB0_2762

.LBB0_2789:
	s_or_b64 exec, exec, s[8:9]
	s_waitcnt vmcnt(0)
.LBB0_2790:
	s_andn2_saveexec_b64 s[6:7], s[6:7]
	s_cbranch_execz .LBB0_2810
	s_mov_b64 s[6:7], exec
	buffer_wbl2 sc1
	s_waitcnt lgkmcnt(0)
	s_waitcnt vmcnt(0)
	v_mbcnt_lo_u32_b32 v1, s6, 0
	v_mbcnt_hi_u32_b32 v1, s7, v1
	v_cmp_eq_u32_e32 vcc, 0, v1
	s_and_saveexec_b64 s[8:9], vcc
	s_cbranch_execz .LBB0_2793
	s_bcnt1_i32_b64 s6, s[6:7]
	v_mov_b32_e32 v2, 0x3000
	v_mov_b32_e32 v3, s6
	global_atomic_add v2, v2, v3, s[96:97] offset:1024 sc0

.LBB0_2809:
	s_or_b64 exec, exec, s[8:9]
.LBB0_2810:
	s_or_b64 exec, exec, s[2:3]
	s_waitcnt lgkmcnt(0)
	s_barrier

.Lfn_done:
.LBB0_2815:
	s_cmp_lt_i32 s87, 19
	s_cselect_b64 s[0:1], -1, 0
	s_xor_b64 s[2:3], s[2:3], -1
	s_or_b64 s[0:1], s[2:3], s[0:1]
	s_and_b64 vcc, exec, s[0:1]
	s_cbranch_vccnz .LBB0_2869
	s_waitcnt vmcnt(0)
	s_waitcnt vmcnt(0)
	s_barrier
	s_mov_b64 s[0:1], exec
	v_readlane_b32 s2, v251, 1
	v_readlane_b32 s3, v251, 2
	s_and_b64 s[2:3], s[0:1], s[2:3]
	s_mov_b64 exec, s[2:3]
	s_cbranch_execz .LBB0_2868
	s_add_i32 s2, 0, 0x23fc0
	v_mov_b32_e32 v0, s2
	s_waitcnt vmcnt(0) expcnt(0) lgkmcnt(0)
	buffer_inv sc1
	ds_read_b32 v2, v0
	s_add_i32 s2, 0, 0x23fc4
	v_mov_b32_e32 v0, s2
	ds_read_b32 v0, v0
	s_waitcnt lgkmcnt(1)
	v_cmp_ne_u32_e32 vcc, 0, v2
	s_cbranch_vccnz .LBB0_2832
	v_readlane_b32 s2, v251, 0
	s_mul_i32 s16, s93, s2
	s_add_u32 s2, s96, 0x1000
	s_addc_u32 s3, s97, 0
	s_add_u32 s4, s96, 0x1100
	s_addc_u32 s5, s97, 0
	s_add_u32 s6, s96, 0x1200
	s_addc_u32 s7, s97, 0
	s_add_u32 s8, s96, 0x1300
	s_mul_i32 s16, s16, s92
	s_addc_u32 s9, s97, 0
	s_mov_b32 s17, 1
	v_mov_b32_e32 v16, 0
	s_branch .LBB0_2820

.LBB0_2847:
	s_or_b64 exec, exec, s[6:7]
	s_waitcnt vmcnt(0)
.LBB0_2848:
	s_andn2_saveexec_b64 s[4:5], s[4:5]
	s_cbranch_execz .LBB0_2868
	s_mov_b64 s[4:5], exec
	buffer_wbl2 sc1
	s_waitcnt lgkmcnt(0)
	s_waitcnt vmcnt(0)
	v_mbcnt_lo_u32_b32 v1, s4, 0
	v_mbcnt_hi_u32_b32 v1, s5, v1
	v_cmp_eq_u32_e32 vcc, 0, v1
	s_and_saveexec_b64 s[6:7], vcc
	s_cbranch_execz .LBB0_2851
	s_bcnt1_i32_b64 s4, s[4:5]
	v_mov_b32_e32 v2, 0x3000
	v_mov_b32_e32 v3, s4
	global_atomic_add v2, v2, v3, s[96:97] offset:1024 sc0

.LBB0_2867:
	s_or_b64 exec, exec, s[6:7]
.LBB0_2868:
	s_or_b64 exec, exec, s[0:1]
	s_waitcnt lgkmcnt(0)
	s_barrier
